# prompt band attention: bias table padded once per item, 16 clamped single reads per key tile replaced by 8 ds_read2_b32 at immediate offsets
# speedup vs baseline: 1.3201x; 1.0017x over previous
.LBB0_865:
	s_or_b64 exec, exec, s[0:1]
	s_lshl_b32 s2, s15, 2
	v_readlane_b32 s4, v254, 45
	v_readlane_b32 s5, v254, 46
	s_add_u32 s2, s4, s2
	s_addc_u32 s3, s5, 0
	s_load_dword s2, s[2:3], 0x800
	v_lshlrev_b32_e32 v112, 2, v18
	v_cmp_gt_u32_e32 vcc, 0x140, v18
	s_mov_b32 s3, 0x3fb8aa3b
	s_waitcnt lgkmcnt(0)
	v_mov_b32_e32 v113, s2
	v_mul_f32_e32 v113, s3, v113
	s_and_saveexec_b64 s[4:5], vcc
	ds_write_b32 v112, v113 offset:22532
	s_or_b64 exec, exec, s[4:5]
	s_or_b32 s1, s13, 1
	s_sub_i32 s0, s13, s17
	s_sub_i32 s3, s1, s17
	s_or_b32 s0, s0, 1
	s_sub_i32 s2, s16, s17
	s_add_i32 s1, s3, 1
	s_lshl_b32 s15, s12, 6
	s_min_i32 s21, s2, 0
	s_max_i32 s16, s0, s1
	s_cmp_lt_i32 s21, s16
	v_lshlrev_b32_e32 v66, 2, v31
	s_cbranch_scc0 .LBB0_1039
	s_lshl_b32 s8, s17, 6
	s_or_b32 s4, s11, s8
	v_readlane_b32 s24, v254, 25
	s_mul_i32 s6, s4, 0x300
	v_readlane_b32 s26, v254, 27
	v_readlane_b32 s27, v254, 28
	s_add_u32 s4, s26, s6
	s_addc_u32 s5, s27, 0
	s_lshl_b32 s7, s15, 1
	s_add_u32 s4, s4, s7
	s_addc_u32 s5, s5, 0
	v_readlane_b32 s12, v254, 23
	v_readlane_b32 s13, v254, 24
	s_add_u32 s6, s12, s6
	s_addc_u32 s9, s13, 0
	s_add_u32 s6, s6, s7
	s_addc_u32 s7, s9, 0
	s_sub_i32 s10, s10, s8
	v_ashrrev_i32_e32 v45, 3, v18
	v_lshlrev_b32_e32 v8, 4, v18
	s_lshl_b32 s18, s21, 6
	s_add_i32 s17, s10, 0x7f
	v_and_b32_e32 v16, 0x70, v8
	v_add3_u32 v8, s18, 64, v45
	v_add_u32_e32 v19, s18, v45
	v_min_i32_e32 v12, s17, v8
	v_mov_b64_e32 v[20:21], s[6:7]
	s_movk_i32 s11, 0x300
	v_mov_b64_e32 v[24:25], s[4:5]
	v_min_i32_e32 v19, s17, v19
	v_mad_i64_i32 v[8:9], s[8:9], v12, s11, v[20:21]
	v_mad_i64_i32 v[12:13], s[8:9], v12, s11, v[24:25]
	v_mad_i64_i32 v[20:21], s[8:9], v19, s11, v[20:21]
	v_mad_i64_i32 v[24:25], s[8:9], v19, s11, v[24:25]
	v_lshl_add_u64 v[8:9], v[8:9], 0, v[16:17]
	v_lshl_add_u64 v[12:13], v[12:13], 0, v[16:17]
	v_lshl_add_u64 v[20:21], v[20:21], 0, v[16:17]
	v_lshl_add_u64 v[24:25], v[24:25], 0, v[16:17]
	global_load_dwordx4 v[8:11], v[8:9], off
	v_lshl_add_u64 v[46:47], s[4:5], 0, v[16:17]
	global_load_dwordx4 v[12:15], v[12:13], off
	v_or_b32_e32 v30, v30, v29
	global_load_dwordx4 v[20:23], v[20:21], off
	s_movk_i32 s4, 0x7f
	global_load_dwordx4 v[24:27], v[24:25], off
	v_cmp_lt_i32_e64 s[8:9], s4, v30
	v_mov_b32_e32 v30, s2
	s_movk_i32 s2, 0x100
	v_cmp_gt_u32_e32 vcc, s2, v18
	s_lshl_b32 s3, s3, 6
	v_mov_b32_e32 v18, s1
	v_cndmask_b32_e64 v68, v30, 0, vcc
	v_mov_b32_e32 v30, s0
	v_cndmask_b32_e32 v69, v18, v30, vcc
	v_mov_b32_e32 v18, s3
	v_mov_b32_e32 v30, s10
	v_lshlrev_b32_e32 v19, 3, v31
	v_lshrrev_b32_e32 v31, 2, v28
	v_cndmask_b32_e32 v18, v18, v30, vcc
	s_movk_i32 s0, 0xa0
	v_or_b32_e32 v31, v66, v31
	v_lshl_add_u64 v[48:49], s[6:7], 0, v[16:17]
	v_mad_u64_u32 v[50:51], s[0:1], v45, s0, v[16:17]
	v_add3_u32 v16, v18, v29, v28
	v_mul_u32_u24_e32 v31, 0xa0, v31
	v_lshlrev_b32_e32 v32, 3, v28
	v_sub_u32_e32 v16, v16, v66
	v_and_or_b32 v31, v32, 24, v31
	v_lshlrev_b32_e32 v51, 1, v19
	v_subrev_u32_e32 v16, s18, v16
	v_mov_b32_e32 v18, v17
	v_mov_b32_e32 v19, v17
	v_add_u32_e32 v67, 0x2800, v31
	v_mul_u32_u24_e32 v80, 0xa0, v28
	v_add_u32_e32 v81, 0x3c00, v31
	v_subrev_u32_e32 v82, 51, v16
	v_mov_b32_e32 v16, v17
	v_mov_b64_e32 v[34:35], v[18:19]
	v_mov_b64_e32 v[42:43], v[18:19]
	v_mov_b64_e32 v[38:39], v[18:19]
	v_mov_b64_e32 v[30:31], v[18:19]
	s_add_i32 s19, s10, 0x80
	v_mov_b32_e32 v84, 0xff800000
	v_mov_b32_e32 v83, 0
	v_mov_b64_e32 v[32:33], v[16:17]
	v_mov_b64_e32 v[40:41], v[16:17]
	v_mov_b64_e32 v[36:37], v[16:17]
	v_mov_b64_e32 v[28:29], v[16:17]
	v_readlane_b32 s25, v254, 26
	s_waitcnt vmcnt(0)

.LBB0_872:
	v_add_u32_e32 v16, v51, v80
	ds_read_b128 v[52:55], v16
	ds_read_b128 v[56:59], v16 offset:64
	ds_read_b128 v[60:63], v16 offset:2560
	ds_read_b128 v[86:89], v16 offset:2624
	ds_read_b128 v[90:93], v16 offset:5120
	ds_read_b128 v[94:97], v16 offset:5184
	s_waitcnt lgkmcnt(5)
	v_mfma_f32_16x16x32_bf16 v[52:55], v[52:55], v[0:3], 0
	s_waitcnt lgkmcnt(3)
	v_mfma_f32_16x16x32_bf16 v[60:63], v[60:63], v[0:3], 0
	v_mfma_f32_16x16x32_bf16 v[52:55], v[56:59], v[4:7], v[52:55]
	ds_read_b128 v[56:59], v16 offset:7680
	ds_read_b128 v[98:101], v16 offset:7744
	s_waitcnt lgkmcnt(4)
	v_mfma_f32_16x16x32_bf16 v[86:89], v[86:89], v[4:7], v[60:63]
	s_waitcnt lgkmcnt(3)
	v_mfma_f32_16x16x32_bf16 v[60:63], v[90:93], v[0:3], 0
	s_waitcnt lgkmcnt(2)
	v_mfma_f32_16x16x32_bf16 v[90:93], v[94:97], v[4:7], v[60:63]
	s_cmp_lt_i32 s18, s19
	s_waitcnt lgkmcnt(1)
	v_mfma_f32_16x16x32_bf16 v[56:59], v[56:59], v[0:3], 0
	s_waitcnt lgkmcnt(0)
	v_mfma_f32_16x16x32_bf16 v[94:97], v[98:101], v[4:7], v[56:59]
	v_lshlrev_b32_e32 v112, 2, v82
	v_add_u32_e32 v112, 0x5400, v112
	ds_read2_b32 v[18:19], v112 offset0:51 offset1:50
	ds_read2_b32 v[56:57], v112 offset0:49 offset1:48
	ds_read2_b32 v[60:61], v112 offset0:35 offset1:34
	ds_read2_b32 v[58:59], v112 offset0:33 offset1:32
	ds_read2_b32 v[98:99], v112 offset0:19 offset1:18
	ds_read2_b32 v[100:101], v112 offset0:17 offset1:16
	ds_read2_b32 v[102:103], v112 offset0:3 offset1:2
	ds_read2_b32 v[104:105], v112 offset0:1 offset1:0
	s_waitcnt lgkmcnt(6)
	v_pk_add_f32 v[62:63], v[54:55], v[56:57]
	v_pk_add_f32 v[64:65], v[52:53], v[18:19]
	s_waitcnt lgkmcnt(4)
	v_pk_add_f32 v[58:59], v[88:89], v[58:59]
	v_pk_add_f32 v[60:61], v[86:87], v[60:61]
	s_waitcnt lgkmcnt(2)
	v_pk_add_f32 v[52:53], v[92:93], v[100:101]
	v_pk_add_f32 v[54:55], v[90:91], v[98:99]
	s_waitcnt lgkmcnt(0)
	v_pk_add_f32 v[18:19], v[96:97], v[104:105]
	v_pk_add_f32 v[56:57], v[94:95], v[102:103]
	s_cbranch_scc1 .LBB0_874
	v_add_u32_e32 v16, s18, v66
	v_add_u32_e32 v87, 3, v16
	v_add_u32_e32 v88, 16, v16
	v_add_u32_e32 v86, 2, v16
	v_cmp_gt_i32_e64 s[4:5], s19, v87
	v_cmp_gt_i32_e64 s[6:7], s19, v88
	v_add_u32_e32 v85, 1, v16
	v_cmp_gt_i32_e64 s[2:3], s19, v86
	s_or_b64 s[4:5], s[6:7], s[4:5]
	v_cmp_gt_i32_e64 s[0:1], s19, v85
	s_or_b64 s[2:3], s[4:5], s[2:3]
	v_cmp_gt_i32_e32 vcc, s19, v16
	s_or_b64 s[0:1], s[2:3], s[0:1]
	v_add_u32_e32 v89, 17, v16
	s_or_b64 vcc, s[0:1], vcc
	v_add_u32_e32 v90, 18, v16
	v_cndmask_b32_e32 v64, v76, v64, vcc
	v_cmp_gt_i32_e32 vcc, s19, v89
	v_add_u32_e32 v91, 19, v16
	v_add_u32_e32 v92, 32, v16
	v_cndmask_b32_e32 v61, v76, v61, vcc
	v_cmp_gt_i32_e32 vcc, s19, v90
	v_cndmask_b32_e64 v65, v76, v65, s[0:1]
	v_cmp_gt_i32_e64 s[0:1], s19, v92
	v_cndmask_b32_e32 v58, v76, v58, vcc
	v_cmp_gt_i32_e32 vcc, s19, v91
	v_add_u32_e32 v93, 33, v16
	s_or_b64 vcc, s[0:1], vcc
	v_add_u32_e32 v94, 34, v16
	v_cndmask_b32_e32 v59, v76, v59, vcc
	v_cmp_gt_i32_e32 vcc, s19, v93
	v_add_u32_e32 v95, 35, v16
	v_add_u32_e32 v96, 48, v16
	v_cndmask_b32_e32 v55, v76, v55, vcc
	v_cmp_gt_i32_e32 vcc, s19, v94
	v_cndmask_b32_e64 v54, v76, v54, s[0:1]
	v_cmp_gt_i32_e64 s[0:1], s19, v96
	v_cndmask_b32_e32 v52, v76, v52, vcc
	v_cmp_gt_i32_e32 vcc, s19, v95
	v_add_u32_e32 v97, 49, v16
	s_or_b64 vcc, s[0:1], vcc
	v_add_u32_e32 v98, 50, v16
	v_cndmask_b32_e32 v53, v76, v53, vcc
	v_cmp_gt_i32_e32 vcc, s19, v97
	v_add_u32_e32 v99, 51, v16
	v_cndmask_b32_e64 v60, v76, v60, s[6:7]
	v_cndmask_b32_e32 v57, v76, v57, vcc
	v_cmp_gt_i32_e32 vcc, s19, v98
	v_cndmask_b32_e64 v63, v76, v63, s[4:5]
	v_cndmask_b32_e64 v62, v76, v62, s[2:3]
	v_cndmask_b32_e32 v18, v76, v18, vcc
	v_cmp_gt_i32_e32 vcc, s19, v99
	v_cndmask_b32_e64 v56, v76, v56, s[0:1]
	s_nop 0
	v_cndmask_b32_e32 v19, v76, v19, vcc

.LBB0_877:
	v_cmp_lt_i32_e32 vcc, s0, v68
	v_cmp_ge_i32_e64 s[0:1], s0, v69
	s_or_b64 s[0:1], vcc, s[0:1]
	s_nor_b64 s[0:1], s[8:9], s[0:1]
	s_and_saveexec_b64 s[12:13], s[0:1]
	s_cbranch_execz .LBB0_881
	v_add_u32_e32 v16, v51, v80
	ds_read_b128 v[52:55], v16
	ds_read_b128 v[56:59], v16 offset:64
	ds_read_b128 v[60:63], v16 offset:2560
	ds_read_b128 v[86:89], v16 offset:2624
	ds_read_b128 v[90:93], v16 offset:5120
	s_waitcnt lgkmcnt(4)
	v_mfma_f32_16x16x32_bf16 v[52:55], v[52:55], v[0:3], 0
	s_waitcnt lgkmcnt(2)
	v_mfma_f32_16x16x32_bf16 v[60:63], v[60:63], v[0:3], 0
	v_mfma_f32_16x16x32_bf16 v[52:55], v[56:59], v[4:7], v[52:55]
	ds_read_b128 v[56:59], v16 offset:5184
	ds_read_b128 v[94:97], v16 offset:7680
	ds_read_b128 v[98:101], v16 offset:7744
	s_waitcnt lgkmcnt(4)
	v_mfma_f32_16x16x32_bf16 v[86:89], v[86:89], v[4:7], v[60:63]
	s_waitcnt lgkmcnt(3)
	v_mfma_f32_16x16x32_bf16 v[60:63], v[90:93], v[0:3], 0
	s_waitcnt lgkmcnt(2)
	v_mfma_f32_16x16x32_bf16 v[90:93], v[56:59], v[4:7], v[60:63]
	s_add_i32 s0, s18, 64
	s_waitcnt lgkmcnt(1)
	v_mfma_f32_16x16x32_bf16 v[56:59], v[94:97], v[0:3], 0
	s_waitcnt lgkmcnt(0)
	v_mfma_f32_16x16x32_bf16 v[94:97], v[98:101], v[4:7], v[56:59]
	v_lshlrev_b32_e32 v112, 2, v82
	v_add_u32_e32 v112, 0x5300, v112
	ds_read2_b32 v[18:19], v112 offset0:51 offset1:50
	ds_read2_b32 v[56:57], v112 offset0:49 offset1:48
	ds_read2_b32 v[60:61], v112 offset0:35 offset1:34
	ds_read2_b32 v[58:59], v112 offset0:33 offset1:32
	ds_read2_b32 v[98:99], v112 offset0:19 offset1:18
	ds_read2_b32 v[100:101], v112 offset0:17 offset1:16
	ds_read2_b32 v[102:103], v112 offset0:3 offset1:2
	ds_read2_b32 v[104:105], v112 offset0:1 offset1:0
	s_waitcnt lgkmcnt(6)
	v_pk_add_f32 v[62:63], v[54:55], v[56:57]
	v_pk_add_f32 v[64:65], v[52:53], v[18:19]
	s_waitcnt lgkmcnt(4)
	v_pk_add_f32 v[58:59], v[88:89], v[58:59]
	v_pk_add_f32 v[60:61], v[86:87], v[60:61]
	s_waitcnt lgkmcnt(2)
	v_pk_add_f32 v[52:53], v[92:93], v[100:101]
	v_pk_add_f32 v[54:55], v[90:91], v[98:99]
	s_waitcnt lgkmcnt(0)
	v_pk_add_f32 v[18:19], v[96:97], v[104:105]
	s_cmp_lt_i32 s0, s19
	v_pk_add_f32 v[56:57], v[94:95], v[102:103]
	s_cbranch_scc1 .LBB0_880
	v_add_u32_e32 v16, s18, v66
	v_add_u32_e32 v88, 0x43, v16
	v_add_u32_e32 v89, 0x50, v16
	v_add_u32_e32 v87, 0x42, v16
	v_cmp_gt_i32_e64 s[4:5], s19, v88
	v_cmp_gt_i32_e64 s[6:7], s19, v89
	v_add_u32_e32 v86, 0x41, v16
	v_cmp_gt_i32_e64 s[2:3], s19, v87
	s_or_b64 s[4:5], s[6:7], s[4:5]
	v_add_u32_e32 v85, 64, v16
	v_cmp_gt_i32_e64 s[0:1], s19, v86
	s_or_b64 s[2:3], s[4:5], s[2:3]
	v_cmp_gt_i32_e32 vcc, s19, v85
	s_or_b64 s[0:1], s[2:3], s[0:1]
	v_add_u32_e32 v90, 0x51, v16
	s_or_b64 vcc, s[0:1], vcc
	v_add_u32_e32 v91, 0x52, v16
	v_cndmask_b32_e32 v64, v76, v64, vcc
	v_cmp_gt_i32_e32 vcc, s19, v90
	v_add_u32_e32 v92, 0x53, v16
	v_add_u32_e32 v93, 0x60, v16
	v_cndmask_b32_e32 v61, v76, v61, vcc
	v_cmp_gt_i32_e32 vcc, s19, v91
	v_cndmask_b32_e64 v65, v76, v65, s[0:1]
	v_cmp_gt_i32_e64 s[0:1], s19, v93
	v_cndmask_b32_e32 v58, v76, v58, vcc
	v_cmp_gt_i32_e32 vcc, s19, v92
	v_add_u32_e32 v94, 0x61, v16
	s_or_b64 vcc, s[0:1], vcc
	v_add_u32_e32 v95, 0x62, v16
	v_cndmask_b32_e32 v59, v76, v59, vcc
	v_cmp_gt_i32_e32 vcc, s19, v94
	v_add_u32_e32 v96, 0x63, v16
	v_add_u32_e32 v97, 0x70, v16
	v_cndmask_b32_e32 v55, v76, v55, vcc
	v_cmp_gt_i32_e32 vcc, s19, v95
	v_cndmask_b32_e64 v54, v76, v54, s[0:1]
	v_cmp_gt_i32_e64 s[0:1], s19, v97
	v_cndmask_b32_e32 v52, v76, v52, vcc
	v_cmp_gt_i32_e32 vcc, s19, v96
	v_add_u32_e32 v98, 0x71, v16
	s_or_b64 vcc, s[0:1], vcc
	v_add_u32_e32 v99, 0x72, v16
	v_cndmask_b32_e32 v53, v76, v53, vcc
	v_cmp_gt_i32_e32 vcc, s19, v98
	v_add_u32_e32 v16, 0x73, v16
	v_cndmask_b32_e64 v60, v76, v60, s[6:7]
	v_cndmask_b32_e32 v57, v76, v57, vcc
	v_cmp_gt_i32_e32 vcc, s19, v99
	v_cndmask_b32_e64 v63, v76, v63, s[4:5]
	v_cndmask_b32_e64 v62, v76, v62, s[2:3]
	v_cndmask_b32_e32 v18, v76, v18, vcc
	v_cmp_gt_i32_e32 vcc, s19, v16
	v_cndmask_b32_e64 v56, v76, v56, s[0:1]
	s_nop 0
	v_cndmask_b32_e32 v19, v76, v19, vcc
